# NSA unit->tile map: early tiles paired mirrored (wq, 63-wq) for equal work per workgroup
# baseline (speedup 1.0000x reference)
.LBB0_983:
	s_cmpk_lg_i32 s84, 0x100
	s_cbranch_scc1 .Lem_skip0
	s_ashr_i32 s3, s2, 3

.LBB0_994:
	s_andn2_b64 vcc, exec, s[0:1]
	s_cbranch_vccnz .LBB0_997
	s_lshr_b32 s75, s63, 1
	s_sub_i32 s98, 63, s75
	s_cmp_eq_u32 s23, 0
	s_cselect_b32 s75, s75, s98
	s_branch .LBB0_997

.LBB0_1004:
	s_andn2_b64 vcc, exec, s[0:1]
	s_cbranch_vccnz .LBB0_1007
	s_lshr_b32 s20, s63, 1
	s_sub_i32 s98, 63, s20
	s_cmp_eq_u32 s21, 0
	s_cselect_b32 s20, s20, s98
	s_branch .LBB0_1007

	.amdhsa_kernel _Z4mega4Args
		.amdhsa_group_segment_fixed_size 0
		.amdhsa_private_segment_fixed_size 0
		.amdhsa_kernarg_size 432
		.amdhsa_user_sgpr_count 2
		.amdhsa_user_sgpr_dispatch_ptr 0
		.amdhsa_user_sgpr_queue_ptr 0
		.amdhsa_user_sgpr_kernarg_segment_ptr 1
		.amdhsa_user_sgpr_dispatch_id 0
		.amdhsa_user_sgpr_kernarg_preload_length 0
		.amdhsa_user_sgpr_kernarg_preload_offset 0
		.amdhsa_user_sgpr_private_segment_size 0
		.amdhsa_uses_dynamic_stack 0
		.amdhsa_enable_private_segment 0
		.amdhsa_system_sgpr_workgroup_id_x 1
		.amdhsa_system_sgpr_workgroup_id_y 0
		.amdhsa_system_sgpr_workgroup_id_z 0
		.amdhsa_system_sgpr_workgroup_info 0
		.amdhsa_system_vgpr_workitem_id 2
		.amdhsa_next_free_vgpr 237
		.amdhsa_next_free_sgpr 100
		.amdhsa_accum_offset 240
		.amdhsa_reserve_vcc 1
		.amdhsa_float_round_mode_32 0
		.amdhsa_float_round_mode_16_64 0
		.amdhsa_float_denorm_mode_32 3
		.amdhsa_float_denorm_mode_16_64 3
		.amdhsa_dx10_clamp 1
		.amdhsa_ieee_mode 1
		.amdhsa_fp16_overflow 0
		.amdhsa_tg_split 0
		.amdhsa_exception_fp_ieee_invalid_op 0
		.amdhsa_exception_fp_denorm_src 0
		.amdhsa_exception_fp_ieee_div_zero 0
		.amdhsa_exception_fp_ieee_overflow 0
		.amdhsa_exception_fp_ieee_underflow 0
		.amdhsa_exception_fp_ieee_inexact 0
		.amdhsa_exception_int_div_zero 0
	.end_amdhsa_kernel

amdhsa.kernels:
  - .agpr_count:     0
    .args:
      - .offset:         0
        .size:           176
        .value_kind:     by_value
      - .offset:         176
        .size:           4
        .value_kind:     hidden_block_count_x
      - .offset:         180
        .size:           4
        .value_kind:     hidden_block_count_y
      - .offset:         184
        .size:           4
        .value_kind:     hidden_block_count_z
      - .offset:         188
        .size:           2
        .value_kind:     hidden_group_size_x
      - .offset:         190
        .size:           2
        .value_kind:     hidden_group_size_y
      - .offset:         192
        .size:           2
        .value_kind:     hidden_group_size_z
      - .offset:         194
        .size:           2
        .value_kind:     hidden_remainder_x
      - .offset:         196
        .size:           2
        .value_kind:     hidden_remainder_y
      - .offset:         198
        .size:           2
        .value_kind:     hidden_remainder_z
      - .offset:         216
        .size:           8
        .value_kind:     hidden_global_offset_x
      - .offset:         224
        .size:           8
        .value_kind:     hidden_global_offset_y
      - .offset:         232
        .size:           8
        .value_kind:     hidden_global_offset_z
      - .offset:         240
        .size:           2
        .value_kind:     hidden_grid_dims
      - .offset:         264
        .size:           8
        .value_kind:     hidden_multigrid_sync_arg
      - .offset:         296
        .size:           4
        .value_kind:     hidden_dynamic_lds_size
    .group_segment_fixed_size: 0
    .kernarg_segment_align: 8
    .kernarg_segment_size: 432
    .language:       OpenCL C
    .language_version:
      - 2
      - 0
    .max_flat_workgroup_size: 512
    .name:           _Z4mega4Args
    .private_segment_fixed_size: 0
    .sgpr_count:     106
    .sgpr_spill_count: 11
    .symbol:         _Z4mega4Args.kd
    .uniform_work_group_size: 1
    .uses_dynamic_stack: false
    .vgpr_count:     237
    .vgpr_spill_count: 0
    .wavefront_size: 64
